# epiboth: hand-written in-proj epilogue for rotary AND plain tiles (z tiles keep compiler path), + kvhwait + tgain
# speedup vs baseline: 1.0070x; 1.0058x over previous
; #define GAS __attribute__((address_space(1)))
; __device__ __forceinline__ unsigned cvt_pk_bf16(float lo, float hi) { unsigned r; asm volatile("v_cvt_pk_bf16_f32 %0, %1, %2" : "=v"(r) : "v"(lo), "v"(hi)); return r; }
;     __device__ __forceinline__ void operator()(const f32x4 (&acc)[2][2][4][2], const Unit& u, int wr, int wc, int fr, int fq, const PG8_LAS float* tab) const {
;     ...
;                 const int row = u.pm * BM + ai * HALF + wr * 64 + m * 16 + fr;
;                 const float rs = rsqrtf(tab[ai * HALF + wr * 64 + m * 16 + fr] * (1.0f / 2048.0f) + 1e-6f);
;                 const int pos = row < 16384 ? (row & 8191) : (row - 16384);
;                 GAS bf16_t* rowp = (GAS bf16_t*)P + (size_t)row * 5120;
;     ...
;                 for (int bj = 0; bj < 2; ++bj) {
;                     const int col0 = pn * BM + bj * HALF + wc * 32 + 8 * fq;
;                     f32x4 v0 = acc[ai][bj][m][0] * rs, v1 = acc[ai][bj][m][1] * rs;
;                     if (is_rope) {
;                         const GAS f32x4* rp = (const GAS f32x4*)((const GAS f32x2*)rope + (size_t)pos * 32 + ((col0 & 63) >> 1));
;                         const f32x4 cs0 = rp[0], cs1 = rp[1];
;                         f32x4 o0, o1;
;                         o0[0] = v0[0] * cs0[0] - v0[1] * cs0[1]; o0[1] = v0[1] * cs0[0] + v0[0] * cs0[1];
;                         o0[2] = v0[2] * cs0[2] - v0[3] * cs0[3]; o0[3] = v0[3] * cs0[2] + v0[2] * cs0[3];
;                         o1[0] = v1[0] * cs1[0] - v1[1] * cs1[1]; o1[1] = v1[1] * cs1[0] + v1[0] * cs1[1];
;                         o1[2] = v1[2] * cs1[2] - v1[3] * cs1[3]; o1[3] = v1[3] * cs1[2] + v1[2] * cs1[3];
;                         v0 = o0 * qs; v1 = o1 * qs;
;                     }
;                     {
;                         u32x4 w; w.x = cvt_pk_bf16(v0[0], v0[1]); w.y = cvt_pk_bf16(v0[2], v0[3]); w.z = cvt_pk_bf16(v1[0], v1[1]); w.w = cvt_pk_bf16(v1[2], v1[3]);
;                         *(GAS u32x4*)(rowp + col0) = w;
;                     }
.Lei_plain_test:
	s_cmp_gt_i32 s0, 17
	s_cbranch_scc1 .Lei_compiler
	s_and_b32 s4, s3, 1
	s_lshl_b32 s4, s4, 10
	v_add_u32_e32 v171, s4, v172
	ds_read_b32 v154, v171 offset:0
	ds_read_b32 v156, v171 offset:64
	ds_read_b32 v158, v171 offset:128
	ds_read_b32 v160, v171 offset:192
	ds_read_b32 v155, v171 offset:512
	ds_read_b32 v157, v171 offset:576
	ds_read_b32 v159, v171 offset:640
	ds_read_b32 v161, v171 offset:704
	s_mul_i32 s4, s1, 0x280000
	s_lshl_b32 s5, s0, 9
	s_add_u32 s4, s4, s5
	s_add_u32 s6, s86, s4
	s_addc_u32 s7, s87, 0
	v_mul_u32_u24_e32 v170, 0x2800, v1
	v_lshl_add_u32 v170, v173, 1, v170
	s_waitcnt lgkmcnt(0)
	v_fmamk_f32 v154, v154, 0x3a000000, v236
	v_fmamk_f32 v156, v156, 0x3a000000, v236
	v_fmamk_f32 v158, v158, 0x3a000000, v236
	v_fmamk_f32 v160, v160, 0x3a000000, v236
	v_fmamk_f32 v155, v155, 0x3a000000, v236
	v_fmamk_f32 v157, v157, 0x3a000000, v236
	v_fmamk_f32 v159, v159, 0x3a000000, v236
	v_fmamk_f32 v161, v161, 0x3a000000, v236
	v_rsq_f32_e32 v154, v154
	v_rsq_f32_e32 v156, v156
	v_rsq_f32_e32 v158, v158
	v_rsq_f32_e32 v160, v160
	v_rsq_f32_e32 v155, v155
	v_rsq_f32_e32 v157, v157
	v_rsq_f32_e32 v159, v159
	v_rsq_f32_e32 v161, v161
	v_pk_mul_f32 v[126:127], v[126:127], v[154:155] op_sel_hi:[1,0]
	v_pk_mul_f32 v[128:129], v[128:129], v[154:155] op_sel_hi:[1,0]
	v_pk_mul_f32 v[122:123], v[122:123], v[154:155] op_sel_hi:[1,0]
	v_pk_mul_f32 v[124:125], v[124:125], v[154:155] op_sel_hi:[1,0]
	v_cvt_pk_bf16_f32 v162, v126, v127
	v_cvt_pk_bf16_f32 v163, v128, v129
	v_cvt_pk_bf16_f32 v164, v122, v123
	v_cvt_pk_bf16_f32 v165, v124, v125
	s_mov_b64 s[10:11], s[6:7]
	global_store_dwordx4 v170, v[162:165], s[10:11] offset:0
	v_pk_mul_f32 v[118:119], v[118:119], v[154:155] op_sel_hi:[1,0]
	v_pk_mul_f32 v[120:121], v[120:121], v[154:155] op_sel_hi:[1,0]
	v_pk_mul_f32 v[114:115], v[114:115], v[154:155] op_sel_hi:[1,0]
	v_pk_mul_f32 v[116:117], v[116:117], v[154:155] op_sel_hi:[1,0]
	v_cvt_pk_bf16_f32 v166, v118, v119
	v_cvt_pk_bf16_f32 v167, v120, v121
	v_cvt_pk_bf16_f32 v168, v114, v115
	v_cvt_pk_bf16_f32 v169, v116, v117
	global_store_dwordx4 v170, v[166:169], s[10:11] offset:256
	v_pk_mul_f32 v[110:111], v[110:111], v[156:157] op_sel_hi:[1,0]
	v_pk_mul_f32 v[112:113], v[112:113], v[156:157] op_sel_hi:[1,0]
	v_pk_mul_f32 v[106:107], v[106:107], v[156:157] op_sel_hi:[1,0]
	v_pk_mul_f32 v[108:109], v[108:109], v[156:157] op_sel_hi:[1,0]
	v_cvt_pk_bf16_f32 v162, v110, v111
	v_cvt_pk_bf16_f32 v163, v112, v113
	v_cvt_pk_bf16_f32 v164, v106, v107
	v_cvt_pk_bf16_f32 v165, v108, v109
	s_add_u32 s10, s6, 0x28000
	s_addc_u32 s11, s7, 0
	global_store_dwordx4 v170, v[162:165], s[10:11] offset:0
	v_pk_mul_f32 v[102:103], v[102:103], v[156:157] op_sel_hi:[1,0]
	v_pk_mul_f32 v[104:105], v[104:105], v[156:157] op_sel_hi:[1,0]
	v_pk_mul_f32 v[98:99], v[98:99], v[156:157] op_sel_hi:[1,0]
	v_pk_mul_f32 v[100:101], v[100:101], v[156:157] op_sel_hi:[1,0]
	v_cvt_pk_bf16_f32 v166, v102, v103
	v_cvt_pk_bf16_f32 v167, v104, v105
	v_cvt_pk_bf16_f32 v168, v98, v99
	v_cvt_pk_bf16_f32 v169, v100, v101
	global_store_dwordx4 v170, v[166:169], s[10:11] offset:256
	v_pk_mul_f32 v[94:95], v[94:95], v[158:159] op_sel_hi:[1,0]
	v_pk_mul_f32 v[96:97], v[96:97], v[158:159] op_sel_hi:[1,0]
	v_pk_mul_f32 v[90:91], v[90:91], v[158:159] op_sel_hi:[1,0]
	v_pk_mul_f32 v[92:93], v[92:93], v[158:159] op_sel_hi:[1,0]
	v_cvt_pk_bf16_f32 v162, v94, v95
	v_cvt_pk_bf16_f32 v163, v96, v97
	v_cvt_pk_bf16_f32 v164, v90, v91
	v_cvt_pk_bf16_f32 v165, v92, v93
	s_add_u32 s10, s6, 0x50000
	s_addc_u32 s11, s7, 0
	global_store_dwordx4 v170, v[162:165], s[10:11] offset:0
	v_pk_mul_f32 v[86:87], v[86:87], v[158:159] op_sel_hi:[1,0]
	v_pk_mul_f32 v[88:89], v[88:89], v[158:159] op_sel_hi:[1,0]
	v_pk_mul_f32 v[82:83], v[82:83], v[158:159] op_sel_hi:[1,0]
	v_pk_mul_f32 v[84:85], v[84:85], v[158:159] op_sel_hi:[1,0]
	v_cvt_pk_bf16_f32 v166, v86, v87
	v_cvt_pk_bf16_f32 v167, v88, v89
	v_cvt_pk_bf16_f32 v168, v82, v83
	v_cvt_pk_bf16_f32 v169, v84, v85
	global_store_dwordx4 v170, v[166:169], s[10:11] offset:256
	v_pk_mul_f32 v[78:79], v[78:79], v[160:161] op_sel_hi:[1,0]
	v_pk_mul_f32 v[80:81], v[80:81], v[160:161] op_sel_hi:[1,0]
	v_pk_mul_f32 v[74:75], v[74:75], v[160:161] op_sel_hi:[1,0]
	v_pk_mul_f32 v[76:77], v[76:77], v[160:161] op_sel_hi:[1,0]
	v_cvt_pk_bf16_f32 v162, v78, v79
	v_cvt_pk_bf16_f32 v163, v80, v81
	v_cvt_pk_bf16_f32 v164, v74, v75
; #define GAS __attribute__((address_space(1)))
; __device__ __forceinline__ unsigned cvt_pk_bf16(float lo, float hi) { unsigned r; asm volatile("v_cvt_pk_bf16_f32 %0, %1, %2" : "=v"(r) : "v"(lo), "v"(hi)); return r; }
;     __device__ __forceinline__ void operator()(const f32x4 (&acc)[2][2][4][2], const Unit& u, int wr, int wc, int fr, int fq, const PG8_LAS float* tab) const {
;     ...
;                 const int row = u.pm * BM + ai * HALF + wr * 64 + m * 16 + fr;
;                 const float rs = rsqrtf(tab[ai * HALF + wr * 64 + m * 16 + fr] * (1.0f / 2048.0f) + 1e-6f);
;                 const int pos = row < 16384 ? (row & 8191) : (row - 16384);
;                 GAS bf16_t* rowp = (GAS bf16_t*)P + (size_t)row * 5120;
;     ...
;                 for (int bj = 0; bj < 2; ++bj) {
;                     const int col0 = pn * BM + bj * HALF + wc * 32 + 8 * fq;
;                     f32x4 v0 = acc[ai][bj][m][0] * rs, v1 = acc[ai][bj][m][1] * rs;
;                     if (is_rope) {
;                         const GAS f32x4* rp = (const GAS f32x4*)((const GAS f32x2*)rope + (size_t)pos * 32 + ((col0 & 63) >> 1));
;                         const f32x4 cs0 = rp[0], cs1 = rp[1];
;                         f32x4 o0, o1;
;                         o0[0] = v0[0] * cs0[0] - v0[1] * cs0[1]; o0[1] = v0[1] * cs0[0] + v0[0] * cs0[1];
;                         o0[2] = v0[2] * cs0[2] - v0[3] * cs0[3]; o0[3] = v0[3] * cs0[2] + v0[2] * cs0[3];
;                         o1[0] = v1[0] * cs1[0] - v1[1] * cs1[1]; o1[1] = v1[1] * cs1[0] + v1[0] * cs1[1];
;                         o1[2] = v1[2] * cs1[2] - v1[3] * cs1[3]; o1[3] = v1[3] * cs1[2] + v1[2] * cs1[3];
;                         v0 = o0 * qs; v1 = o1 * qs;
;                     }
;                     {
;                         u32x4 w; w.x = cvt_pk_bf16(v0[0], v0[1]); w.y = cvt_pk_bf16(v0[2], v0[3]); w.z = cvt_pk_bf16(v1[0], v1[1]); w.w = cvt_pk_bf16(v1[2], v1[3]);
;                         *(GAS u32x4*)(rowp + col0) = w;
;                     }
	v_cvt_pk_bf16_f32 v165, v76, v77
	s_add_u32 s10, s6, 0x78000
	s_addc_u32 s11, s7, 0
	global_store_dwordx4 v170, v[162:165], s[10:11] offset:0
	v_pk_mul_f32 v[70:71], v[70:71], v[160:161] op_sel_hi:[1,0]
	v_pk_mul_f32 v[72:73], v[72:73], v[160:161] op_sel_hi:[1,0]
	v_pk_mul_f32 v[66:67], v[66:67], v[160:161] op_sel_hi:[1,0]
	v_pk_mul_f32 v[68:69], v[68:69], v[160:161] op_sel_hi:[1,0]
	v_cvt_pk_bf16_f32 v166, v70, v71
	v_cvt_pk_bf16_f32 v167, v72, v73
	v_cvt_pk_bf16_f32 v168, v66, v67
	v_cvt_pk_bf16_f32 v169, v68, v69
	global_store_dwordx4 v170, v[166:169], s[10:11] offset:256
	v_mov_b32_e32 v154, v155
	v_mov_b32_e32 v156, v157
	v_mov_b32_e32 v158, v159
	v_mov_b32_e32 v160, v161
	v_pk_mul_f32 v[62:63], v[62:63], v[154:155] op_sel_hi:[1,0]
	v_pk_mul_f32 v[64:65], v[64:65], v[154:155] op_sel_hi:[1,0]
	v_pk_mul_f32 v[58:59], v[58:59], v[154:155] op_sel_hi:[1,0]
	v_pk_mul_f32 v[60:61], v[60:61], v[154:155] op_sel_hi:[1,0]
	v_cvt_pk_bf16_f32 v162, v62, v63
	v_cvt_pk_bf16_f32 v163, v64, v65
	v_cvt_pk_bf16_f32 v164, v58, v59
	v_cvt_pk_bf16_f32 v165, v60, v61
	s_add_u32 s10, s6, 0x140000
	s_addc_u32 s11, s7, 0
	global_store_dwordx4 v170, v[162:165], s[10:11] offset:0
	v_pk_mul_f32 v[54:55], v[54:55], v[154:155] op_sel_hi:[1,0]
	v_pk_mul_f32 v[56:57], v[56:57], v[154:155] op_sel_hi:[1,0]
	v_pk_mul_f32 v[50:51], v[50:51], v[154:155] op_sel_hi:[1,0]
	v_pk_mul_f32 v[52:53], v[52:53], v[154:155] op_sel_hi:[1,0]
	v_cvt_pk_bf16_f32 v166, v54, v55
	v_cvt_pk_bf16_f32 v167, v56, v57
	v_cvt_pk_bf16_f32 v168, v50, v51
	v_cvt_pk_bf16_f32 v169, v52, v53
	global_store_dwordx4 v170, v[166:169], s[10:11] offset:256
	v_pk_mul_f32 v[46:47], v[46:47], v[156:157] op_sel_hi:[1,0]
	v_pk_mul_f32 v[48:49], v[48:49], v[156:157] op_sel_hi:[1,0]
	v_pk_mul_f32 v[42:43], v[42:43], v[156:157] op_sel_hi:[1,0]
	v_pk_mul_f32 v[44:45], v[44:45], v[156:157] op_sel_hi:[1,0]
	v_cvt_pk_bf16_f32 v162, v46, v47
	v_cvt_pk_bf16_f32 v163, v48, v49
	v_cvt_pk_bf16_f32 v164, v42, v43
	v_cvt_pk_bf16_f32 v165, v44, v45
	s_add_u32 s10, s6, 0x168000
	s_addc_u32 s11, s7, 0
	global_store_dwordx4 v170, v[162:165], s[10:11] offset:0
	v_pk_mul_f32 v[38:39], v[38:39], v[156:157] op_sel_hi:[1,0]
	v_pk_mul_f32 v[40:41], v[40:41], v[156:157] op_sel_hi:[1,0]
	v_pk_mul_f32 v[34:35], v[34:35], v[156:157] op_sel_hi:[1,0]
	v_pk_mul_f32 v[36:37], v[36:37], v[156:157] op_sel_hi:[1,0]
	v_cvt_pk_bf16_f32 v166, v38, v39
	v_cvt_pk_bf16_f32 v167, v40, v41
	v_cvt_pk_bf16_f32 v168, v34, v35
	v_cvt_pk_bf16_f32 v169, v36, v37
	global_store_dwordx4 v170, v[166:169], s[10:11] offset:256
	v_pk_mul_f32 v[30:31], v[30:31], v[158:159] op_sel_hi:[1,0]
	v_pk_mul_f32 v[32:33], v[32:33], v[158:159] op_sel_hi:[1,0]
	v_pk_mul_f32 v[26:27], v[26:27], v[158:159] op_sel_hi:[1,0]
	v_pk_mul_f32 v[28:29], v[28:29], v[158:159] op_sel_hi:[1,0]
	v_cvt_pk_bf16_f32 v162, v30, v31
	v_cvt_pk_bf16_f32 v163, v32, v33
	v_cvt_pk_bf16_f32 v164, v26, v27
	v_cvt_pk_bf16_f32 v165, v28, v29
	s_add_u32 s10, s6, 0x190000
	s_addc_u32 s11, s7, 0
	global_store_dwordx4 v170, v[162:165], s[10:11] offset:0
	v_pk_mul_f32 v[22:23], v[22:23], v[158:159] op_sel_hi:[1,0]
	v_pk_mul_f32 v[24:25], v[24:25], v[158:159] op_sel_hi:[1,0]
	v_pk_mul_f32 v[18:19], v[18:19], v[158:159] op_sel_hi:[1,0]
	v_pk_mul_f32 v[20:21], v[20:21], v[158:159] op_sel_hi:[1,0]
	v_cvt_pk_bf16_f32 v166, v22, v23
	v_cvt_pk_bf16_f32 v167, v24, v25
	v_cvt_pk_bf16_f32 v168, v18, v19
	v_cvt_pk_bf16_f32 v169, v20, v21
	global_store_dwordx4 v170, v[166:169], s[10:11] offset:256
	v_pk_mul_f32 v[14:15], v[14:15], v[160:161] op_sel_hi:[1,0]
	v_pk_mul_f32 v[16:17], v[16:17], v[160:161] op_sel_hi:[1,0]
	v_pk_mul_f32 v[10:11], v[10:11], v[160:161] op_sel_hi:[1,0]
	v_pk_mul_f32 v[12:13], v[12:13], v[160:161] op_sel_hi:[1,0]
	v_cvt_pk_bf16_f32 v162, v14, v15
	v_cvt_pk_bf16_f32 v163, v16, v17
	v_cvt_pk_bf16_f32 v164, v10, v11
	v_cvt_pk_bf16_f32 v165, v12, v13
	s_add_u32 s10, s6, 0x1b8000
	s_addc_u32 s11, s7, 0
	global_store_dwordx4 v170, v[162:165], s[10:11] offset:0
	v_pk_mul_f32 v[6:7], v[6:7], v[160:161] op_sel_hi:[1,0]
	v_pk_mul_f32 v[8:9], v[8:9], v[160:161] op_sel_hi:[1,0]
	v_pk_mul_f32 v[2:3], v[2:3], v[160:161] op_sel_hi:[1,0]
	v_pk_mul_f32 v[4:5], v[4:5], v[160:161] op_sel_hi:[1,0]
	v_cvt_pk_bf16_f32 v166, v6, v7
	v_cvt_pk_bf16_f32 v167, v8, v9
	v_cvt_pk_bf16_f32 v168, v2, v3
	v_cvt_pk_bf16_f32 v169, v4, v5
	global_store_dwordx4 v170, v[166:169], s[10:11] offset:256
	s_branch .LBB0_406
